# baseline (speedup 1.0000x reference)
; DEVI bf16_t f2bf(float x) { return (bf16_t)(cvtpk(x, x) & 0xffffu); }
; DEVI void prep_phase(const Params& p, char* lds) {
;     ...
;   for (int i = gtid; i < 2 * 4 * 8 * 128 * 128; i += gsz) {
;     const int half = i >= 4 * 8 * 128 * 128, j = i - half * (4 * 8 * 128 * 128);
;     const int lh = j >> 14, rem = j & 16383;
;     WT[WT_KEYS + ((size_t)lh * 2 + half) * 16384 + rem] = f2bf((half ? p.in[I_PK2] : p.in[I_PK1])[j]);
;   }
.LBB0_3267:
	s_mov_b32 s3, 0x7ffff
	v_cmp_lt_i32_e32 vcc, s3, v2
	v_mov_b32_e32 v3, s9
	v_mov_b32_e32 v5, s11
	v_cndmask_b32_e32 v0, 0, v238, vcc
	v_mov_b32_e32 v6, s8
	v_mov_b32_e32 v8, s10
	v_add_u32_e32 v4, v0, v2
	v_cndmask_b32_e32 v7, v3, v5, vcc
	v_cndmask_b32_e32 v6, v6, v8, vcc
	v_ashrrev_i32_e32 v5, 31, v4
	v_lshl_add_u64 v[6:7], v[4:5], 2, v[6:7]
	v_ashrrev_i32_e32 v4, 14, v4
	v_ashrrev_i32_e32 v5, 31, v4
	v_lshlrev_b64 v[4:5], 16, v[4:5]
	global_load_dword v3, v[6:7], off
	v_and_b32_e32 v6, 0x3fff, v2
	v_cndmask_b32_e32 v0, 0, v233, vcc
	v_lshl_add_u64 v[4:5], s[0:1], 0, v[4:5]
	v_add_u32_e32 v2, s2, v2
	s_mov_b32 s3, 0xfffff
	v_lshl_add_u64 v[4:5], v[4:5], 0, v[0:1]
	v_lshlrev_b32_e32 v0, 1, v6
	v_cmp_lt_i32_e32 vcc, s3, v2
	v_lshl_add_u64 v[4:5], v[4:5], 0, v[0:1]
	s_or_b64 s[6:7], vcc, s[6:7]
	v_add_co_u32_e32 v4, vcc, 0x2380000, v4
	s_nop 1
	v_addc_co_u32_e32 v5, vcc, 0, v5, vcc
	s_mov_b64 s[38:39], exec
	s_andn2_b64 exec, exec, s[6:7]
	v_mov_b32_e32 v29, 0
	s_mov_b32 s3, 0x7ffff
	v_cmp_lt_i32_e32 vcc, s3, v2
	v_mov_b32_e32 v20, s9
	v_mov_b32_e32 v23, s11
	v_cndmask_b32_e32 v28, 0, v238, vcc
	v_mov_b32_e32 v24, s8
	v_mov_b32_e32 v26, s10
	v_add_u32_e32 v22, v28, v2
	v_cndmask_b32_e32 v25, v20, v23, vcc
	v_cndmask_b32_e32 v24, v24, v26, vcc
	v_ashrrev_i32_e32 v23, 31, v22
	v_lshl_add_u64 v[24:25], v[22:23], 2, v[24:25]
	v_ashrrev_i32_e32 v22, 14, v22
	v_ashrrev_i32_e32 v23, 31, v22
	v_lshlrev_b64 v[22:23], 16, v[22:23]
	global_load_dword v20, v[24:25], off
	v_and_b32_e32 v24, 0x3fff, v2
	v_cndmask_b32_e32 v28, 0, v233, vcc
	v_lshl_add_u64 v[22:23], s[0:1], 0, v[22:23]
	v_add_u32_e32 v2, s2, v2
	s_mov_b32 s3, 0xfffff
	v_lshl_add_u64 v[22:23], v[22:23], 0, v[28:29]
	v_lshlrev_b32_e32 v28, 1, v24
	v_cmp_lt_i32_e32 vcc, s3, v2
	v_lshl_add_u64 v[22:23], v[22:23], 0, v[28:29]
	s_or_b64 s[6:7], vcc, s[6:7]
	v_add_co_u32_e32 v22, vcc, 0x2380000, v22
	s_nop 1
	v_addc_co_u32_e32 v23, vcc, 0, v23, vcc
	s_waitcnt vmcnt(0)
	v_cvt_pk_bf16_f32 v28, v20, v20
	global_store_short v[22:23], v28, off
	s_mov_b64 exec, s[38:39]
	v_cvt_pk_bf16_f32 v0, v3, v3
	global_store_short v[4:5], v0, off
	s_andn2_b64 exec, exec, s[6:7]
	s_cbranch_execnz .LBB0_3267
